# layer-1 ffn_down weight bf16 transposition moved from phase-0 pass 2 to the idle WGs (bid>=128) in the tail round of the layer-0 SwiGLU GEMM phase
# speedup vs baseline: 1.0067x; 1.0022x over previous
; __device__ __forceinline__ void xpose_item(const float* src, int ld, bf16_t* dst, int K, int k0, LAS float* scr, int lane, const float* gk) {
;     if (src) {
; #pragma unroll 8
;         for (int i = 0; i < 32; ++i) { const int kk = 2 * i + (lane >> 5); scr[kk * 33 + (lane & 31)] = __builtin_nontemporal_load(src + (size_t)(k0 + kk) * ld + (lane & 31)); }
;     } else {
; #pragma unroll 8
;         for (int i = 0; i < 32; ++i) { const int kk = 2 * i + (lane >> 5); scr[kk * 33 + (lane & 31)] = 0.f; }
;     }
;     const int c = lane & 7;
;     f32x4 g0 = (f32x4){1.f, 1.f, 1.f, 1.f}, g1 = g0;
;     if (gk) { g0 = *(const f32x4*)(gk + k0 + 8 * c); g1 = *(const f32x4*)(gk + k0 + 8 * c + 4); }
;     asm volatile("s_waitcnt lgkmcnt(0)" ::: "memory");
; #pragma unroll
;     for (int j = 0; j < 4; ++j) { const int n = (lane >> 3) + 8 * j; const LAS float* s = scr + (8 * c) * 33 + n;
;         u32x4 o; o.x = cvt_pk_bf16(s[0 * 33] * g0[0], s[1 * 33] * g0[1]); o.y = cvt_pk_bf16(s[2 * 33] * g0[2], s[3 * 33] * g0[3]); o.z = cvt_pk_bf16(s[4 * 33] * g1[0], s[5 * 33] * g1[1]); o.w = cvt_pk_bf16(s[6 * 33] * g1[2], s[7 * 33] * g1[3]);
;         *(u32x4*)(dst + (size_t)n * K + k0 + 8 * c) = o; }
;     asm volatile("s_waitcnt lgkmcnt(0)" ::: "memory");
; }
; __device__ __forceinline__ int xpose_all(const float* src, const float* src2, int ld, int K, int ndst, int nsrc, int mode, bf16_t* dst, int it, int NGW, LAS float* scr, int lane, const float* gvec = nullptr) {
;     const int nblk = ndst / 32, nitems = (K / 64) * nblk;
;     for (; it < nitems; it += NGW) {
;         const int kb = it / nblk, nb = it % nblk, n0 = nb * 32; const float* sp;
;         if (mode == 0) sp = (n0 < nsrc) ? src + n0 : nullptr;
;         else if (mode == 1) { const int unit = n0 >> 8, bj = (n0 >> 7) & 1, cl = n0 & 127; sp = (bj ? src2 : src) + unit * 128 + cl; }
;         else if (mode == 3) { const int pn = n0 >> 8, cl = n0 & 255; sp = src + ((pn >> 2) & 1) * 2048 + ((pn & 3) + 4 * (pn >> 3)) * 256 + cl; }
;         else { const int unit = n0 >> 8, bj = (n0 >> 7) & 1, cl = n0 & 127; sp = (bj ? src2 : src) + (size_t)(unit >> 1) * 65536 + (unit & 1) * 128 + cl; }
;         xpose_item(sp, ld, dst + (size_t)n0 * K, K, kb * 64, scr, lane, gvec);
; __global__ void __launch_bounds__(512) mega(Args a_byval) {
;     ...
;         case 7: case 19: if (!PH_ON(7)) break; {
.LBB0_418:
	s_waitcnt vmcnt(0)
	s_barrier
	s_cmp_lg_u32 s76, 7
	s_cbranch_scc1 .Lf7_done
	v_readlane_b32 s59, v255, 5
	s_cmpk_lg_i32 s59, 0x100
	s_cbranch_scc1 .Lf7_done
	s_cmpk_lt_i32 s94, 0x80
	s_cbranch_scc1 .Lf7_done
	s_load_dwordx2 s[60:61], s[92:93], 0xc8
	s_load_dwordx2 s[62:63], s[92:93], 0xe8
	s_sub_i32 s59, s94, 0x80
	s_lshl_b32 s59, s59, 3
	s_add_i32 s59, s59, s95
	s_mul_i32 s64, s95, 0x2100
	v_and_b32_e32 v2, 31, v200
	v_lshrrev_b32_e32 v3, 5, v200
	v_lshlrev_b32_e32 v4, 2, v2
	v_lshl_add_u32 v5, v3, 13, v4
	v_mul_u32_u24_e32 v6, 0x84, v3
	v_add3_u32 v6, v6, v4, s64
	v_and_b32_e32 v7, 7, v200
	v_lshrrev_b32_e32 v8, 3, v200
	v_mul_u32_u24_e32 v9, 0x420, v7
	v_lshl_add_u32 v9, v8, 2, v9
	v_add_u32_e32 v9, s64, v9
	v_mul_u32_u24_e32 v10, 0x2c00, v8
	v_lshl_add_u32 v12, v7, 4, v10
	v_add_u32_e32 v13, 0x16000, v12
	v_add_u32_e32 v14, 0x2c000, v12
	v_add_u32_e32 v15, 0x42000, v12
	s_waitcnt lgkmcnt(0)
	s_add_u32 s60, s60, 0x2c00000
	s_addc_u32 s61, s61, 0
	s_add_u32 s62, s62, 0x6500000
	s_addc_u32 s63, s63, 0
; #define LAS __attribute__((address_space(3)))
; __device__ __forceinline__ unsigned cvt_pk_bf16(float lo, float hi) { unsigned r; asm volatile("v_cvt_pk_bf16_f32 %0, %1, %2" : "=v"(r) : "v"(lo), "v"(hi)); return r; }
; __device__ __forceinline__ void xpose_item(const float* src, int ld, bf16_t* dst, int K, int k0, LAS float* scr, int lane, const float* gk) {
;     if (src) {
; #pragma unroll 8
;         for (int i = 0; i < 32; ++i) { const int kk = 2 * i + (lane >> 5); scr[kk * 33 + (lane & 31)] = __builtin_nontemporal_load(src + (size_t)(k0 + kk) * ld + (lane & 31)); }
;     } else {
; #pragma unroll 8
;         for (int i = 0; i < 32; ++i) { const int kk = 2 * i + (lane >> 5); scr[kk * 33 + (lane & 31)] = 0.f; }
;     }
;     const int c = lane & 7;
;     f32x4 g0 = (f32x4){1.f, 1.f, 1.f, 1.f}, g1 = g0;
;     if (gk) { g0 = *(const f32x4*)(gk + k0 + 8 * c); g1 = *(const f32x4*)(gk + k0 + 8 * c + 4); }
;     asm volatile("s_waitcnt lgkmcnt(0)" ::: "memory");
; #pragma unroll
;     for (int j = 0; j < 4; ++j) { const int n = (lane >> 3) + 8 * j; const LAS float* s = scr + (8 * c) * 33 + n;
;         u32x4 o; o.x = cvt_pk_bf16(s[0 * 33] * g0[0], s[1 * 33] * g0[1]); o.y = cvt_pk_bf16(s[2 * 33] * g0[2], s[3 * 33] * g0[3]); o.z = cvt_pk_bf16(s[4 * 33] * g1[0], s[5 * 33] * g1[1]); o.w = cvt_pk_bf16(s[6 * 33] * g1[2], s[7 * 33] * g1[3]);
;         *(u32x4*)(dst + (size_t)n * K + k0 + 8 * c) = o; }
;     asm volatile("s_waitcnt lgkmcnt(0)" ::: "memory");
; }
.Lf7_item:
	s_lshr_b32 s64, s59, 6
	s_and_b32 s65, s59, 63
	s_lshl_b32 s66, s64, 19
	s_lshl_b32 s67, s65, 7
	s_add_i32 s66, s66, s67
	s_add_u32 s66, s60, s66
	s_addc_u32 s67, s61, 0
	v_mov_b32_e32 v11, v5
	global_load_dword v20, v11, s[66:67] nt
	v_add_u32_e32 v11, 0x4000, v11
	global_load_dword v21, v11, s[66:67] nt
	v_add_u32_e32 v11, 0x4000, v11
	global_load_dword v22, v11, s[66:67] nt
	v_add_u32_e32 v11, 0x4000, v11
	global_load_dword v23, v11, s[66:67] nt
	v_add_u32_e32 v11, 0x4000, v11
	global_load_dword v24, v11, s[66:67] nt
	v_add_u32_e32 v11, 0x4000, v11
	global_load_dword v25, v11, s[66:67] nt
	v_add_u32_e32 v11, 0x4000, v11
	global_load_dword v26, v11, s[66:67] nt
	v_add_u32_e32 v11, 0x4000, v11
	global_load_dword v27, v11, s[66:67] nt
	v_add_u32_e32 v11, 0x4000, v11
	global_load_dword v28, v11, s[66:67] nt
	v_add_u32_e32 v11, 0x4000, v11
	global_load_dword v29, v11, s[66:67] nt
	v_add_u32_e32 v11, 0x4000, v11
	global_load_dword v30, v11, s[66:67] nt
	v_add_u32_e32 v11, 0x4000, v11
	global_load_dword v31, v11, s[66:67] nt
	v_add_u32_e32 v11, 0x4000, v11
	global_load_dword v32, v11, s[66:67] nt
	v_add_u32_e32 v11, 0x4000, v11
	global_load_dword v33, v11, s[66:67] nt
	v_add_u32_e32 v11, 0x4000, v11
	global_load_dword v34, v11, s[66:67] nt
	v_add_u32_e32 v11, 0x4000, v11
	global_load_dword v35, v11, s[66:67] nt
	v_add_u32_e32 v11, 0x4000, v11
	global_load_dword v36, v11, s[66:67] nt
	v_add_u32_e32 v11, 0x4000, v11
	global_load_dword v37, v11, s[66:67] nt
	v_add_u32_e32 v11, 0x4000, v11
	global_load_dword v38, v11, s[66:67] nt
	v_add_u32_e32 v11, 0x4000, v11
	global_load_dword v39, v11, s[66:67] nt
	v_add_u32_e32 v11, 0x4000, v11
	global_load_dword v40, v11, s[66:67] nt
	v_add_u32_e32 v11, 0x4000, v11
	global_load_dword v41, v11, s[66:67] nt
	v_add_u32_e32 v11, 0x4000, v11
	global_load_dword v42, v11, s[66:67] nt
	v_add_u32_e32 v11, 0x4000, v11
	global_load_dword v43, v11, s[66:67] nt
	v_add_u32_e32 v11, 0x4000, v11
	global_load_dword v44, v11, s[66:67] nt
	v_add_u32_e32 v11, 0x4000, v11
	global_load_dword v45, v11, s[66:67] nt
	v_add_u32_e32 v11, 0x4000, v11
	global_load_dword v46, v11, s[66:67] nt
	v_add_u32_e32 v11, 0x4000, v11
	global_load_dword v47, v11, s[66:67] nt
	v_add_u32_e32 v11, 0x4000, v11
	global_load_dword v48, v11, s[66:67] nt
	v_add_u32_e32 v11, 0x4000, v11
	global_load_dword v49, v11, s[66:67] nt
	v_add_u32_e32 v11, 0x4000, v11
	global_load_dword v50, v11, s[66:67] nt
	v_add_u32_e32 v11, 0x4000, v11
	global_load_dword v51, v11, s[66:67] nt
	s_mul_i32 s68, s65, 0x58000
	s_lshl_b32 s64, s64, 7
	s_add_i32 s68, s68, s64
	s_add_u32 s64, s62, s68
	s_addc_u32 s65, s63, 0
	s_waitcnt vmcnt(31)
	ds_write_b32 v6, v20 offset:0
	s_waitcnt vmcnt(30)
	ds_write_b32 v6, v21 offset:264
	s_waitcnt vmcnt(29)
	ds_write_b32 v6, v22 offset:528
	s_waitcnt vmcnt(28)
	ds_write_b32 v6, v23 offset:792
	s_waitcnt vmcnt(27)
	ds_write_b32 v6, v24 offset:1056
	s_waitcnt vmcnt(26)
	ds_write_b32 v6, v25 offset:1320
	s_waitcnt vmcnt(25)
	ds_write_b32 v6, v26 offset:1584
	s_waitcnt vmcnt(24)
	ds_write_b32 v6, v27 offset:1848
	s_waitcnt vmcnt(23)
	ds_write_b32 v6, v28 offset:2112
	s_waitcnt vmcnt(22)
	ds_write_b32 v6, v29 offset:2376
	s_waitcnt vmcnt(21)
	ds_write_b32 v6, v30 offset:2640
	s_waitcnt vmcnt(20)
	ds_write_b32 v6, v31 offset:2904
	s_waitcnt vmcnt(19)
	ds_write_b32 v6, v32 offset:3168
	s_waitcnt vmcnt(18)
	ds_write_b32 v6, v33 offset:3432
	s_waitcnt vmcnt(17)
	ds_write_b32 v6, v34 offset:3696
	s_waitcnt vmcnt(16)
	ds_write_b32 v6, v35 offset:3960
	s_waitcnt vmcnt(15)
	ds_write_b32 v6, v36 offset:4224
	s_waitcnt vmcnt(14)
	ds_write_b32 v6, v37 offset:4488
	s_waitcnt vmcnt(13)
	ds_write_b32 v6, v38 offset:4752
	s_waitcnt vmcnt(12)
	ds_write_b32 v6, v39 offset:5016
	s_waitcnt vmcnt(11)
	ds_write_b32 v6, v40 offset:5280
	s_waitcnt vmcnt(10)
	ds_write_b32 v6, v41 offset:5544
	s_waitcnt vmcnt(9)
	ds_write_b32 v6, v42 offset:5808
	s_waitcnt vmcnt(8)
	ds_write_b32 v6, v43 offset:6072
	s_waitcnt vmcnt(7)
	ds_write_b32 v6, v44 offset:6336
	s_waitcnt vmcnt(6)
	ds_write_b32 v6, v45 offset:6600
	s_waitcnt vmcnt(5)
	ds_write_b32 v6, v46 offset:6864
	s_waitcnt vmcnt(4)
	ds_write_b32 v6, v47 offset:7128
	s_waitcnt vmcnt(3)
	ds_write_b32 v6, v48 offset:7392
	s_waitcnt vmcnt(2)
	ds_write_b32 v6, v49 offset:7656
	s_waitcnt vmcnt(1)
	ds_write_b32 v6, v50 offset:7920
	s_waitcnt vmcnt(0)
	ds_write_b32 v6, v51 offset:8184
	s_waitcnt lgkmcnt(0)
	ds_read2_b32 v[60:61], v9 offset0:0 offset1:33
	ds_read2_b32 v[62:63], v9 offset0:66 offset1:99
	ds_read2_b32 v[64:65], v9 offset0:132 offset1:165
	ds_read2_b32 v[66:67], v9 offset0:198 offset1:231
	ds_read2_b32 v[68:69], v9 offset0:8 offset1:41
	ds_read2_b32 v[70:71], v9 offset0:74 offset1:107
	ds_read2_b32 v[72:73], v9 offset0:140 offset1:173
	ds_read2_b32 v[74:75], v9 offset0:206 offset1:239
	ds_read2_b32 v[76:77], v9 offset0:16 offset1:49
	ds_read2_b32 v[78:79], v9 offset0:82 offset1:115
	ds_read2_b32 v[80:81], v9 offset0:148 offset1:181
	ds_read2_b32 v[82:83], v9 offset0:214 offset1:247
	ds_read2_b32 v[84:85], v9 offset0:24 offset1:57
	ds_read2_b32 v[86:87], v9 offset0:90 offset1:123
	ds_read2_b32 v[88:89], v9 offset0:156 offset1:189
	ds_read2_b32 v[90:91], v9 offset0:222 offset1:255
	s_waitcnt lgkmcnt(12)
	v_cvt_pk_bf16_f32 v92, v60, v61
	v_cvt_pk_bf16_f32 v93, v62, v63
	v_cvt_pk_bf16_f32 v94, v64, v65
	v_cvt_pk_bf16_f32 v95, v66, v67
	global_store_dwordx4 v12, v[92:95], s[64:65]
	s_waitcnt lgkmcnt(8)
	v_cvt_pk_bf16_f32 v96, v68, v69
	v_cvt_pk_bf16_f32 v97, v70, v71
	v_cvt_pk_bf16_f32 v98, v72, v73
	v_cvt_pk_bf16_f32 v99, v74, v75
	global_store_dwordx4 v13, v[96:99], s[64:65]
	s_waitcnt lgkmcnt(4)
	v_cvt_pk_bf16_f32 v100, v76, v77
	v_cvt_pk_bf16_f32 v101, v78, v79
	v_cvt_pk_bf16_f32 v102, v80, v81
	v_cvt_pk_bf16_f32 v103, v82, v83
	global_store_dwordx4 v14, v[100:103], s[64:65]
	s_waitcnt lgkmcnt(0)
	v_cvt_pk_bf16_f32 v104, v84, v85
	v_cvt_pk_bf16_f32 v105, v86, v87
	v_cvt_pk_bf16_f32 v106, v88, v89
	v_cvt_pk_bf16_f32 v107, v90, v91
	global_store_dwordx4 v15, v[104:107], s[64:65]
	s_addk_i32 s59, 0x400
	s_cmpk_lt_i32 s59, 0x1600
	s_cbranch_scc1 .Lf7_item
	s_waitcnt vmcnt(0)
.Lf7_done:
	s_load_dwordx2 s[38:39], s[92:93], 0xe8
	s_mov_b32 s18, 0x16c02000
	s_mov_b32 s19, 0x16c04000
	s_mov_b32 s20, 0x16c06000
	s_mov_b32 s21, 0x16c07000
	s_mov_b32 s22, 0x1ac07000
	s_mov_b32 s23, 0x10c03000

; #define LAS __attribute__((address_space(3)))
; __device__ __forceinline__ int xpose_all(const float* src, const float* src2, int ld, int K, int ndst, int nsrc, int mode, bf16_t* dst, int it, int NGW, LAS float* scr, int lane, const float* gvec = nullptr) {
;     const int nblk = ndst / 32, nitems = (K / 64) * nblk;
;     for (; it < nitems; it += NGW) {
;         const int kb = it / nblk, nb = it % nblk, n0 = nb * 32; const float* sp;
;         if (mode == 0) sp = (n0 < nsrc) ? src + n0 : nullptr;
;         else if (mode == 1) { const int unit = n0 >> 8, bj = (n0 >> 7) & 1, cl = n0 & 127; sp = (bj ? src2 : src) + unit * 128 + cl; }
;         else if (mode == 3) { const int pn = n0 >> 8, cl = n0 & 255; sp = src + ((pn >> 2) & 1) * 2048 + ((pn & 3) + 4 * (pn >> 3)) * 256 + cl; }
;         else { const int unit = n0 >> 8, bj = (n0 >> 7) & 1, cl = n0 & 127; sp = (bj ? src2 : src) + (size_t)(unit >> 1) * 65536 + (unit & 1) * 128 + cl; }
;         xpose_item(sp, ld, dst + (size_t)n0 * K, K, kb * 64, scr, lane, gvec);
;     }
;     return it - nitems;
; }
; __global__ void __launch_bounds__(512) mega(Args a_byval) {
;     ...
;                 it = xpose_all(a.in[22], nullptr, 2048, 4096, 2048, 2048, 0, (bf16_t*)(ws + WS_WB_OUT), it, NGW, scr, lane);
;             }
;             it = xpose_all(a.in[23] + (size_t)lyr * D * DFF, a.in[24] + (size_t)lyr * D * DFF, DFF, 2048, 2 * DFF, 2 * DFF, 1, (bf16_t*)(ws + (lyr ? WS_W_GU : WS_W_GU0)), it, NGW, scr, lane, norm_ffn_g + lyr * D);
;             it = xpose_all(a.in[25] + (size_t)lyr * D * DFF, nullptr, 2048, DFF, 2048, 2048, 0, (bf16_t*)(ws + (lyr ? WS_W_D : WS_W_D0)), it, NGW, scr, lane);
.LBB0_658:
	s_add_i32 s11, s28, 0xffffd400
	s_cmp_lg_u32 s76, 12
	s_cbranch_scc1 .Lf7_noskip
	v_readlane_b32 vcc_lo, v255, 5
	s_cmpk_lg_i32 vcc_lo, 0x100
	s_cbranch_scc1 .Lf7_noskip
	s_addk_i32 s11, 0x1600
	s_branch .LBB0_669
.Lf7_noskip:
	s_cmpk_gt_u32 s11, 0x15ff
	s_cbranch_scc1 .LBB0_669
	s_load_dwordx2 s[0:1], s[92:93], 0xc8
	s_add_u32 s13, s38, s16
	v_lshlrev_b32_e32 v2, 2, v11
	v_mov_b32_e32 v3, v0
	v_lshlrev_b32_e32 v1, 2, v212
	v_lshrrev_b32_e32 v5, 3, v211
	s_addc_u32 s20, s39, s17
	s_waitcnt lgkmcnt(0)
	v_lshl_add_u64 v[6:7], s[0:1], 0, v[2:3]
	v_lshrrev_b32_e32 v2, 5, v211
	v_and_b32_e32 v8, 0x7c, v1
	v_and_b32_e32 v1, 7, v212
	v_lshlrev_b32_e32 v3, 2, v5
	v_mul_u32_u24_e32 v12, 0x1600, v5
	v_mov_b32_e32 v5, s26
	v_lshlrev_b32_e32 v10, 3, v1
	v_mul_u32_u24_e32 v1, 0x420, v1
	s_cmp_lg_u64 s[0:1], 0
	v_mov_b32_e32 v9, v0
	v_mad_u32_u24 v5, v2, s33, v5
	v_add_u32_e32 v4, s27, v8
	v_add3_u32 v3, s27, v1, v3
	s_cselect_b64 s[0:1], -1, 0
	v_lshl_add_u64 v[6:7], v[6:7], 0, v[8:9]
	v_mov_b32_e32 v1, v2
	v_add3_u32 v5, v5, v8, 0
	v_lshlrev_b32_e32 v8, 1, v10
	v_lshlrev_b32_e32 v10, 1, v12
	s_branch .LBB0_661
